# EpiResid epilogue: each row group waits only for its own two residual loads (vmcnt 14+g) instead of all sixteen
# speedup vs baseline: 1.0024x; 1.0024x over previous
; __device__ __forceinline__ unsigned cvt_pk_bf16(float lo, float hi) { unsigned r; asm volatile("v_cvt_pk_bf16_f32 %0, %1, %2" : "=v"(r) : "v"(lo), "v"(hi)); return r; }
;     __device__ __forceinline__ void operator()(const f32x4 (&acc)[2][2][4][2], const Unit& u, int wr, int wc, int fr, int fq) const {
;         const int row0 = u.pm * BM + wr * 64 + fr, col0 = u.pn * BM + wc * 32 + 8 * fq;
;         u32x4 hv[2][4][2];
; #pragma unroll
;         for (int ai = 0; ai < 2; ++ai)
; #pragma unroll
;             for (int m = 0; m < 4; ++m)
; #pragma unroll
;                 for (int bj = 0; bj < 2; ++bj) hv[ai][m][bj] = *(const u32x4*)(hb + (size_t)(row0 + ai * HALF + m * 16) * 1024 + col0 + bj * HALF);
; #pragma unroll
;         for (int ai = 0; ai < 2; ++ai)
; #pragma unroll
;             for (int m = 0; m < 4; ++m) { const int row = row0 + ai * HALF + m * 16; float s = 0.f;
; #pragma unroll
;                 for (int bj = 0; bj < 2; ++bj) { const size_t off = (size_t)row * 1024 + col0 + bj * HALF;
;                     const u32x4 h4 = hv[ai][m][bj];
;                     const f32x4 b0 = {__uint_as_float(h4.x << 16), __uint_as_float(h4.x & 0xffff0000u), __uint_as_float(h4.y << 16), __uint_as_float(h4.y & 0xffff0000u)};
;                     const f32x4 b1 = {__uint_as_float(h4.z << 16), __uint_as_float(h4.z & 0xffff0000u), __uint_as_float(h4.w << 16), __uint_as_float(h4.w & 0xffff0000u)};
;                     const f32x4 v0 = acc[ai][bj][m][0] + b0, v1 = acc[ai][bj][m][1] + b1;
;                     u32x4 w; w.x = cvt_pk_bf16(v0[0], v0[1]); w.y = cvt_pk_bf16(v0[2], v0[3]); w.z = cvt_pk_bf16(v1[0], v1[1]); w.w = cvt_pk_bf16(v1[2], v1[3]);
;                     *(u32x4*)(hb + off) = w;
;                     s += ((v0[0] * v0[0] + v0[1] * v0[1]) + (v0[2] * v0[2] + v0[3] * v0[3])) + ((v1[0] * v1[0] + v1[1] * v1[1]) + (v1[2] * v1[2] + v1[3] * v1[3])); }
;                 s += __shfl_xor(s, 16); s += __shfl_xor(s, 32);
;                 if (fq == 0) ssq[(size_t)row * 16 + u.pn * 4 + wc] = s; }
.LBB0_323:
	v_lshl_or_b32 v204, s12, 8, v253
	v_lshl_add_u32 v240, s61, 8, v251
	v_ashrrev_i32_e32 v205, 31, v204
	v_lshlrev_b64 v[242:243], 1, v[204:205]
	v_ashrrev_i32_e32 v241, 31, v240
	v_lshl_add_u64 v[122:123], s[58:59], 0, v[242:243]
	v_lshlrev_b64 v[244:245], 11, v[240:241]
	v_lshl_add_u64 v[114:115], v[122:123], 0, v[244:245]
	global_load_dwordx4 v[190:193], v[114:115], off
	global_load_dwordx4 v[186:189], v[114:115], off offset:256
	v_or_b32_e32 v236, 16, v240
	v_ashrrev_i32_e32 v237, 31, v236
	v_or_b32_e32 v232, 32, v240
	v_lshlrev_b64 v[238:239], 11, v[236:237]
	v_ashrrev_i32_e32 v233, 31, v232
	v_or_b32_e32 v228, 48, v240
	v_lshl_add_u64 v[114:115], v[122:123], 0, v[238:239]
	v_lshlrev_b64 v[234:235], 11, v[232:233]
	v_ashrrev_i32_e32 v229, 31, v228
	v_add_u32_e32 v224, 0x80, v240
	global_load_dwordx4 v[182:185], v[114:115], off
	global_load_dwordx4 v[178:181], v[114:115], off offset:256
	v_lshl_add_u64 v[114:115], v[122:123], 0, v[234:235]
	v_lshlrev_b64 v[230:231], 11, v[228:229]
	v_ashrrev_i32_e32 v225, 31, v224
	v_add_u32_e32 v220, 0x90, v240
	global_load_dwordx4 v[174:177], v[114:115], off
	global_load_dwordx4 v[170:173], v[114:115], off offset:256
	v_lshl_add_u64 v[114:115], v[122:123], 0, v[230:231]
	v_lshlrev_b64 v[226:227], 11, v[224:225]
	v_ashrrev_i32_e32 v221, 31, v220
	v_add_u32_e32 v216, 0xa0, v240
	v_add_u32_e32 v212, 0xb0, v240
	global_load_dwordx4 v[166:169], v[114:115], off
	global_load_dwordx4 v[162:165], v[114:115], off offset:256
	v_lshl_add_u64 v[114:115], v[122:123], 0, v[226:227]
	v_lshlrev_b64 v[222:223], 11, v[220:221]
	v_ashrrev_i32_e32 v217, 31, v216
	v_ashrrev_i32_e32 v213, 31, v212
	global_load_dwordx4 v[158:161], v[114:115], off
	global_load_dwordx4 v[146:149], v[114:115], off offset:256
	v_lshl_add_u64 v[114:115], v[122:123], 0, v[222:223]
	v_lshlrev_b64 v[218:219], 11, v[216:217]
	v_lshlrev_b64 v[214:215], 11, v[212:213]
	global_load_dwordx4 v[142:145], v[114:115], off
	global_load_dwordx4 v[138:141], v[114:115], off offset:256
	v_lshl_add_u64 v[114:115], v[122:123], 0, v[218:219]
	v_lshl_add_u64 v[122:123], v[122:123], 0, v[214:215]
	global_load_dwordx4 v[126:129], v[114:115], off
	s_nop 0
	global_load_dwordx4 v[114:117], v[114:115], off offset:256
	s_nop 0
	global_load_dwordx4 v[130:133], v[122:123], off
	s_nop 0
	global_load_dwordx4 v[122:125], v[122:123], off offset:256
	s_lshl_b32 s86, s12, 2
	s_ashr_i32 s87, s86, 31
	s_waitcnt vmcnt(14)
	v_lshlrev_b32_e32 v208, 16, v190
	v_and_b32_e32 v209, 0xffff0000, v190
	v_lshlrev_b32_e32 v190, 16, v191
	v_and_b32_e32 v191, 0xffff0000, v191
	v_lshlrev_b32_e32 v210, 16, v192
	v_and_b32_e32 v211, 0xffff0000, v192
	v_lshlrev_b32_e32 v192, 16, v193
	v_and_b32_e32 v193, 0xffff0000, v193
	v_pk_add_f32 v[154:155], v[154:155], v[208:209]
	v_lshl_add_u64 v[208:209], s[58:59], 0, v[244:245]
	v_pk_add_f32 v[156:157], v[156:157], v[190:191]
	v_pk_add_f32 v[190:191], v[152:153], v[192:193]
	v_pk_add_f32 v[192:193], v[150:151], v[210:211]
	v_cvt_pk_bf16_f32 v150, v154, v155
	v_cvt_pk_bf16_f32 v151, v156, v157
	v_lshl_add_u64 v[208:209], v[208:209], 0, v[242:243]
	v_cvt_pk_bf16_f32 v152, v192, v193
	v_cvt_pk_bf16_f32 v153, v190, v191
	global_store_dwordx4 v[208:209], v[150:153], off
	s_nop 1
	v_mul_f32_e32 v150, v155, v155
	v_mul_f32_e32 v151, v157, v157
	v_fmac_f32_e32 v150, v154, v154
	v_fmac_f32_e32 v151, v156, v156
	v_add_f32_e32 v150, v150, v151
	v_mul_f32_e32 v151, v193, v193
	v_mul_f32_e32 v152, v191, v191
	v_fmac_f32_e32 v151, v192, v192
	v_fmac_f32_e32 v152, v190, v190
	v_add_f32_e32 v151, v151, v152
	v_add_f32_e32 v190, v150, v151
	v_lshlrev_b32_e32 v150, 16, v186
	v_and_b32_e32 v151, 0xffff0000, v186
	v_lshlrev_b32_e32 v152, 16, v187
	v_and_b32_e32 v153, 0xffff0000, v187
	v_lshlrev_b32_e32 v154, 16, v188
	v_and_b32_e32 v155, 0xffff0000, v188
	v_lshlrev_b32_e32 v156, 16, v189
	v_and_b32_e32 v157, 0xffff0000, v189
	v_pk_add_f32 v[136:137], v[136:137], v[152:153]
	v_pk_add_f32 v[134:135], v[134:135], v[150:151]
	v_pk_add_f32 v[152:153], v[118:119], v[154:155]
	v_cvt_pk_bf16_f32 v118, v134, v135
	v_cvt_pk_bf16_f32 v119, v136, v137
	v_pk_add_f32 v[150:151], v[120:121], v[156:157]
	v_cvt_pk_bf16_f32 v120, v152, v153
	s_nop 0
	v_cvt_pk_bf16_f32 v121, v150, v151
	global_store_dwordx4 v[208:209], v[118:121], off offset:256
	s_nop 1
	v_mul_f32_e32 v118, v135, v135
	v_mul_f32_e32 v119, v137, v137
	v_fmac_f32_e32 v118, v134, v134
	v_fmac_f32_e32 v119, v136, v136
	v_add_f32_e32 v118, v118, v119
	v_mul_f32_e32 v119, v153, v153
	v_mul_f32_e32 v120, v151, v151
	v_fmac_f32_e32 v119, v152, v152
	v_fmac_f32_e32 v120, v150, v150
	v_add_f32_e32 v119, v119, v120
	v_add_f32_e32 v118, v118, v119
	v_and_b32_e32 v120, 64, v246
	v_add_f32_e32 v119, v190, v118
	v_xor_b32_e32 v118, 16, v246
	v_add_u32_e32 v121, 64, v120
	v_cmp_lt_i32_e32 vcc, v118, v121
	s_nop 1
	v_cndmask_b32_e32 v118, v246, v118, vcc
	v_lshlrev_b32_e32 v118, 2, v118
	v_mov_b32_e32 v120, v119
	s_nop 1
	v_permlane16_swap_b32_e32 v119, v120
	s_waitcnt lgkmcnt(0)
	v_add_f32_e32 v120, v119, v120
	v_xor_b32_e32 v119, 32, v246
	v_cmp_lt_i32_e32 vcc, v119, v121
	s_nop 1
	v_cndmask_b32_e32 v119, v246, v119, vcc
	v_lshlrev_b32_e32 v119, 2, v119
	v_mov_b32_e32 v121, v120
	s_nop 1
	v_permlane32_swap_b32_e32 v120, v121
	s_and_saveexec_b64 s[88:89], s[4:5]
	s_cbranch_execz .LBB0_325
	s_waitcnt lgkmcnt(0)
	v_add_f32_e32 v134, v120, v121
	v_lshlrev_b64 v[120:121], 6, v[240:241]
	v_lshl_add_u64 v[120:121], s[56:57], 0, v[120:121]
	v_lshl_add_u64 v[120:121], s[86:87], 2, v[120:121]
	s_lshl_b32 s12, s29, 2
	v_lshl_add_u64 v[120:121], v[120:121], 0, s[12:13]
	global_store_dword v[120:121], v134, off
; __device__ __forceinline__ unsigned cvt_pk_bf16(float lo, float hi) { unsigned r; asm volatile("v_cvt_pk_bf16_f32 %0, %1, %2" : "=v"(r) : "v"(lo), "v"(hi)); return r; }
;     __device__ __forceinline__ void operator()(const f32x4 (&acc)[2][2][4][2], const Unit& u, int wr, int wc, int fr, int fq) const {
;     ...
;             for (int m = 0; m < 4; ++m) { const int row = row0 + ai * HALF + m * 16; float s = 0.f;
; #pragma unroll
;                 for (int bj = 0; bj < 2; ++bj) { const size_t off = (size_t)row * 1024 + col0 + bj * HALF;
;                     const u32x4 h4 = hv[ai][m][bj];
;                     const f32x4 b0 = {__uint_as_float(h4.x << 16), __uint_as_float(h4.x & 0xffff0000u), __uint_as_float(h4.y << 16), __uint_as_float(h4.y & 0xffff0000u)};
;                     const f32x4 b1 = {__uint_as_float(h4.z << 16), __uint_as_float(h4.z & 0xffff0000u), __uint_as_float(h4.w << 16), __uint_as_float(h4.w & 0xffff0000u)};
;                     const f32x4 v0 = acc[ai][bj][m][0] + b0, v1 = acc[ai][bj][m][1] + b1;
;                     u32x4 w; w.x = cvt_pk_bf16(v0[0], v0[1]); w.y = cvt_pk_bf16(v0[2], v0[3]); w.z = cvt_pk_bf16(v1[0], v1[1]); w.w = cvt_pk_bf16(v1[2], v1[3]);
;                     *(u32x4*)(hb + off) = w;
;                     s += ((v0[0] * v0[0] + v0[1] * v0[1]) + (v0[2] * v0[2] + v0[3] * v0[3])) + ((v1[0] * v1[0] + v1[1] * v1[1]) + (v1[2] * v1[2] + v1[3] * v1[3])); }
;                 s += __shfl_xor(s, 16); s += __shfl_xor(s, 32);
;                 if (fq == 0) ssq[(size_t)row * 16 + u.pn * 4 + wc] = s; }
.LBB0_325:
	s_or_b64 exec, exec, s[88:89]
	s_waitcnt vmcnt(15)
	v_lshlrev_b32_e32 v120, 16, v182
	s_waitcnt lgkmcnt(0)
	v_and_b32_e32 v121, 0xffff0000, v182
	v_lshlrev_b32_e32 v134, 16, v183
	v_and_b32_e32 v135, 0xffff0000, v183
	v_lshlrev_b32_e32 v136, 16, v184
	v_and_b32_e32 v137, 0xffff0000, v184
	v_pk_add_f32 v[110:111], v[110:111], v[120:121]
	v_pk_add_f32 v[112:113], v[112:113], v[134:135]
	v_pk_add_f32 v[134:135], v[106:107], v[136:137]
	v_cvt_pk_bf16_f32 v106, v110, v111
	v_mul_f32_e32 v111, v111, v111
	v_lshlrev_b32_e32 v150, 16, v185
	v_and_b32_e32 v151, 0xffff0000, v185
	v_fmac_f32_e32 v111, v110, v110
	v_mul_f32_e32 v110, v113, v113
	v_pk_add_f32 v[120:121], v[108:109], v[150:151]
	v_fmac_f32_e32 v110, v112, v112
	v_cvt_pk_bf16_f32 v107, v112, v113
	v_add_f32_e32 v110, v111, v110
	v_mul_f32_e32 v111, v135, v135
	v_mul_f32_e32 v112, v121, v121
	v_fmac_f32_e32 v111, v134, v134
	v_fmac_f32_e32 v112, v120, v120
	v_add_f32_e32 v111, v111, v112
	v_add_f32_e32 v136, v110, v111
	v_lshlrev_b32_e32 v110, 16, v178
	v_and_b32_e32 v111, 0xffff0000, v178
	v_lshlrev_b32_e32 v112, 16, v179
	v_and_b32_e32 v113, 0xffff0000, v179
	v_cvt_pk_bf16_f32 v108, v134, v135
	v_cvt_pk_bf16_f32 v109, v120, v121
	v_lshlrev_b32_e32 v120, 16, v180
	v_and_b32_e32 v121, 0xffff0000, v180
	v_pk_add_f32 v[104:105], v[104:105], v[112:113]
	v_pk_add_f32 v[102:103], v[102:103], v[110:111]
	v_lshlrev_b32_e32 v134, 16, v181
	v_and_b32_e32 v135, 0xffff0000, v181
	v_pk_add_f32 v[112:113], v[98:99], v[120:121]
	v_mul_f32_e32 v98, v103, v103
	v_mul_f32_e32 v99, v105, v105
	v_pk_add_f32 v[110:111], v[100:101], v[134:135]
	v_fmac_f32_e32 v98, v102, v102
	v_fmac_f32_e32 v99, v104, v104
	v_add_f32_e32 v98, v98, v99
	v_mul_f32_e32 v99, v113, v113
	v_mul_f32_e32 v100, v111, v111
	v_fmac_f32_e32 v99, v112, v112
	v_fmac_f32_e32 v100, v110, v110
	v_add_f32_e32 v99, v99, v100
	v_add_f32_e32 v98, v98, v99
	v_add_f32_e32 v101, v136, v98
	v_mov_b32_e32 v134, v101
	s_nop 1
	v_permlane16_swap_b32_e32 v101, v134
	v_lshl_add_u64 v[98:99], s[58:59], 0, v[238:239]
	v_lshl_add_u64 v[120:121], v[204:205], 1, v[98:99]
	global_store_dwordx4 v[120:121], v[106:109], off
	v_cvt_pk_bf16_f32 v100, v102, v103
	s_waitcnt lgkmcnt(0)
	v_add_f32_e32 v98, v101, v134
	v_mov_b32_e32 v99, v98
	s_nop 1
	v_permlane32_swap_b32_e32 v98, v99
	v_cvt_pk_bf16_f32 v101, v104, v105
	v_cvt_pk_bf16_f32 v102, v112, v113
	v_cvt_pk_bf16_f32 v103, v110, v111
	global_store_dwordx4 v[120:121], v[100:103], off offset:256
	s_and_saveexec_b64 s[88:89], s[4:5]
	s_cbranch_execz .LBB0_327
	s_waitcnt lgkmcnt(0)
	v_add_f32_e32 v100, v98, v99
	v_lshlrev_b64 v[98:99], 6, v[236:237]
	v_lshl_add_u64 v[98:99], s[56:57], 0, v[98:99]
	v_lshl_add_u64 v[98:99], s[86:87], 2, v[98:99]
	s_lshl_b32 s12, s29, 2
	v_lshl_add_u64 v[98:99], v[98:99], 0, s[12:13]
	global_store_dword v[98:99], v100, off
.LBB0_327:
	s_or_b64 exec, exec, s[88:89]
	s_waitcnt vmcnt(16)
	v_lshlrev_b32_e32 v98, 16, v174
	s_waitcnt lgkmcnt(0)
	v_and_b32_e32 v99, 0xffff0000, v174
	v_lshlrev_b32_e32 v100, 16, v175
	v_and_b32_e32 v101, 0xffff0000, v175
	v_lshlrev_b32_e32 v102, 16, v176
	v_and_b32_e32 v103, 0xffff0000, v176
	v_pk_add_f32 v[94:95], v[94:95], v[98:99]
	v_pk_add_f32 v[96:97], v[96:97], v[100:101]
	v_pk_add_f32 v[100:101], v[90:91], v[102:103]
	v_cvt_pk_bf16_f32 v90, v94, v95
	v_mul_f32_e32 v95, v95, v95
	v_lshlrev_b32_e32 v104, 16, v177
	v_and_b32_e32 v105, 0xffff0000, v177
	v_fmac_f32_e32 v95, v94, v94
	v_mul_f32_e32 v94, v97, v97
	v_pk_add_f32 v[98:99], v[92:93], v[104:105]
	v_fmac_f32_e32 v94, v96, v96
	v_cvt_pk_bf16_f32 v91, v96, v97
	v_add_f32_e32 v94, v95, v94
	v_mul_f32_e32 v95, v101, v101
	v_mul_f32_e32 v96, v99, v99
	v_fmac_f32_e32 v95, v100, v100
	v_fmac_f32_e32 v96, v98, v98
	v_add_f32_e32 v95, v95, v96
	v_add_f32_e32 v102, v94, v95
	v_lshlrev_b32_e32 v94, 16, v170
	v_and_b32_e32 v95, 0xffff0000, v170
	v_lshlrev_b32_e32 v96, 16, v171
	v_and_b32_e32 v97, 0xffff0000, v171
	v_cvt_pk_bf16_f32 v92, v100, v101
	v_cvt_pk_bf16_f32 v93, v98, v99
	v_lshlrev_b32_e32 v98, 16, v172
	v_and_b32_e32 v99, 0xffff0000, v172
	v_pk_add_f32 v[88:89], v[88:89], v[96:97]
	v_pk_add_f32 v[86:87], v[86:87], v[94:95]
	v_lshlrev_b32_e32 v100, 16, v173
	v_and_b32_e32 v101, 0xffff0000, v173
	v_pk_add_f32 v[96:97], v[82:83], v[98:99]
	v_mul_f32_e32 v82, v87, v87
	v_mul_f32_e32 v83, v89, v89
	v_pk_add_f32 v[94:95], v[84:85], v[100:101]
	v_fmac_f32_e32 v82, v86, v86
	v_fmac_f32_e32 v83, v88, v88
	v_add_f32_e32 v82, v82, v83
	v_mul_f32_e32 v83, v97, v97
	v_mul_f32_e32 v84, v95, v95
	v_fmac_f32_e32 v83, v96, v96
	v_fmac_f32_e32 v84, v94, v94
	v_add_f32_e32 v83, v83, v84
	v_add_f32_e32 v82, v82, v83
	v_add_f32_e32 v85, v102, v82
	v_mov_b32_e32 v100, v85
	s_nop 1
	v_permlane16_swap_b32_e32 v85, v100
	v_lshl_add_u64 v[82:83], s[58:59], 0, v[234:235]
	v_lshl_add_u64 v[98:99], v[204:205], 1, v[82:83]
	global_store_dwordx4 v[98:99], v[90:93], off
	v_cvt_pk_bf16_f32 v84, v86, v87
	s_waitcnt lgkmcnt(0)
	v_add_f32_e32 v82, v85, v100
	v_mov_b32_e32 v83, v82
	s_nop 1
	v_permlane32_swap_b32_e32 v82, v83
	v_cvt_pk_bf16_f32 v85, v88, v89
	v_cvt_pk_bf16_f32 v86, v96, v97
	v_cvt_pk_bf16_f32 v87, v94, v95
	global_store_dwordx4 v[98:99], v[84:87], off offset:256
	s_and_saveexec_b64 s[88:89], s[4:5]
	s_cbranch_execz .LBB0_329
	s_waitcnt lgkmcnt(0)
	v_add_f32_e32 v84, v82, v83
	v_lshlrev_b64 v[82:83], 6, v[232:233]
	v_lshl_add_u64 v[82:83], s[56:57], 0, v[82:83]
	v_lshl_add_u64 v[82:83], s[86:87], 2, v[82:83]
	s_lshl_b32 s12, s29, 2
	v_lshl_add_u64 v[82:83], v[82:83], 0, s[12:13]
	global_store_dword v[82:83], v84, off
; __device__ __forceinline__ unsigned cvt_pk_bf16(float lo, float hi) { unsigned r; asm volatile("v_cvt_pk_bf16_f32 %0, %1, %2" : "=v"(r) : "v"(lo), "v"(hi)); return r; }
;     __device__ __forceinline__ void operator()(const f32x4 (&acc)[2][2][4][2], const Unit& u, int wr, int wc, int fr, int fq) const {
;     ...
;             for (int m = 0; m < 4; ++m) { const int row = row0 + ai * HALF + m * 16; float s = 0.f;
; #pragma unroll
;                 for (int bj = 0; bj < 2; ++bj) { const size_t off = (size_t)row * 1024 + col0 + bj * HALF;
;                     const u32x4 h4 = hv[ai][m][bj];
;                     const f32x4 b0 = {__uint_as_float(h4.x << 16), __uint_as_float(h4.x & 0xffff0000u), __uint_as_float(h4.y << 16), __uint_as_float(h4.y & 0xffff0000u)};
;                     const f32x4 b1 = {__uint_as_float(h4.z << 16), __uint_as_float(h4.z & 0xffff0000u), __uint_as_float(h4.w << 16), __uint_as_float(h4.w & 0xffff0000u)};
;                     const f32x4 v0 = acc[ai][bj][m][0] + b0, v1 = acc[ai][bj][m][1] + b1;
;                     u32x4 w; w.x = cvt_pk_bf16(v0[0], v0[1]); w.y = cvt_pk_bf16(v0[2], v0[3]); w.z = cvt_pk_bf16(v1[0], v1[1]); w.w = cvt_pk_bf16(v1[2], v1[3]);
;                     *(u32x4*)(hb + off) = w;
;                     s += ((v0[0] * v0[0] + v0[1] * v0[1]) + (v0[2] * v0[2] + v0[3] * v0[3])) + ((v1[0] * v1[0] + v1[1] * v1[1]) + (v1[2] * v1[2] + v1[3] * v1[3])); }
;                 s += __shfl_xor(s, 16); s += __shfl_xor(s, 32);
;                 if (fq == 0) ssq[(size_t)row * 16 + u.pn * 4 + wc] = s; }
.LBB0_329:
	s_or_b64 exec, exec, s[88:89]
	s_waitcnt vmcnt(17)
	v_lshlrev_b32_e32 v82, 16, v166
	s_waitcnt lgkmcnt(0)
	v_and_b32_e32 v83, 0xffff0000, v166
	v_lshlrev_b32_e32 v84, 16, v167
	v_and_b32_e32 v85, 0xffff0000, v167
	v_lshlrev_b32_e32 v86, 16, v168
	v_and_b32_e32 v87, 0xffff0000, v168
	v_pk_add_f32 v[78:79], v[78:79], v[82:83]
	v_pk_add_f32 v[80:81], v[80:81], v[84:85]
	v_pk_add_f32 v[84:85], v[74:75], v[86:87]
	v_cvt_pk_bf16_f32 v74, v78, v79
	v_mul_f32_e32 v79, v79, v79
	v_lshlrev_b32_e32 v88, 16, v169
	v_and_b32_e32 v89, 0xffff0000, v169
	v_fmac_f32_e32 v79, v78, v78
	v_mul_f32_e32 v78, v81, v81
	v_pk_add_f32 v[82:83], v[76:77], v[88:89]
	v_fmac_f32_e32 v78, v80, v80
	v_cvt_pk_bf16_f32 v75, v80, v81
	v_add_f32_e32 v78, v79, v78
	v_mul_f32_e32 v79, v85, v85
	v_mul_f32_e32 v80, v83, v83
	v_fmac_f32_e32 v79, v84, v84
	v_fmac_f32_e32 v80, v82, v82
	v_add_f32_e32 v79, v79, v80
	v_add_f32_e32 v86, v78, v79
	v_lshlrev_b32_e32 v78, 16, v162
	v_and_b32_e32 v79, 0xffff0000, v162
	v_lshlrev_b32_e32 v80, 16, v163
	v_and_b32_e32 v81, 0xffff0000, v163
	v_cvt_pk_bf16_f32 v76, v84, v85
	v_cvt_pk_bf16_f32 v77, v82, v83
	v_lshlrev_b32_e32 v82, 16, v164
	v_and_b32_e32 v83, 0xffff0000, v164
	v_pk_add_f32 v[72:73], v[72:73], v[80:81]
	v_pk_add_f32 v[70:71], v[70:71], v[78:79]
	v_lshlrev_b32_e32 v84, 16, v165
	v_and_b32_e32 v85, 0xffff0000, v165
	v_pk_add_f32 v[80:81], v[66:67], v[82:83]
	v_mul_f32_e32 v66, v71, v71
	v_mul_f32_e32 v67, v73, v73
	v_pk_add_f32 v[78:79], v[68:69], v[84:85]
	v_fmac_f32_e32 v66, v70, v70
	v_fmac_f32_e32 v67, v72, v72
	v_add_f32_e32 v66, v66, v67
	v_mul_f32_e32 v67, v81, v81
	v_mul_f32_e32 v68, v79, v79
	v_fmac_f32_e32 v67, v80, v80
	v_fmac_f32_e32 v68, v78, v78
	v_add_f32_e32 v67, v67, v68
	v_add_f32_e32 v66, v66, v67
	v_add_f32_e32 v69, v86, v66
	v_mov_b32_e32 v84, v69
	s_nop 1
	v_permlane16_swap_b32_e32 v69, v84
	v_lshl_add_u64 v[66:67], s[58:59], 0, v[230:231]
	v_lshl_add_u64 v[82:83], v[204:205], 1, v[66:67]
	global_store_dwordx4 v[82:83], v[74:77], off
	v_cvt_pk_bf16_f32 v68, v70, v71
	s_waitcnt lgkmcnt(0)
	v_add_f32_e32 v66, v69, v84
	v_mov_b32_e32 v67, v66
	s_nop 1
	v_permlane32_swap_b32_e32 v66, v67
	v_cvt_pk_bf16_f32 v69, v72, v73
	v_cvt_pk_bf16_f32 v70, v80, v81
	v_cvt_pk_bf16_f32 v71, v78, v79
	global_store_dwordx4 v[82:83], v[68:71], off offset:256
	s_and_saveexec_b64 s[88:89], s[4:5]
	s_cbranch_execz .LBB0_331
	s_waitcnt lgkmcnt(0)
	v_add_f32_e32 v68, v66, v67
	v_lshlrev_b64 v[66:67], 6, v[228:229]
	v_lshl_add_u64 v[66:67], s[56:57], 0, v[66:67]
	v_lshl_add_u64 v[66:67], s[86:87], 2, v[66:67]
	s_lshl_b32 s12, s29, 2
	v_lshl_add_u64 v[66:67], v[66:67], 0, s[12:13]
	global_store_dword v[66:67], v68, off
.LBB0_331:
	s_or_b64 exec, exec, s[88:89]
	s_waitcnt vmcnt(18)
	v_lshlrev_b32_e32 v66, 16, v158
	s_waitcnt lgkmcnt(0)
	v_and_b32_e32 v67, 0xffff0000, v158
	v_lshlrev_b32_e32 v68, 16, v159
	v_and_b32_e32 v69, 0xffff0000, v159
	v_lshlrev_b32_e32 v70, 16, v160
	v_and_b32_e32 v71, 0xffff0000, v160
	v_pk_add_f32 v[62:63], v[62:63], v[66:67]
	v_pk_add_f32 v[64:65], v[64:65], v[68:69]
	v_pk_add_f32 v[68:69], v[58:59], v[70:71]
	v_cvt_pk_bf16_f32 v58, v62, v63
	v_mul_f32_e32 v63, v63, v63
	v_lshlrev_b32_e32 v72, 16, v161
	v_and_b32_e32 v73, 0xffff0000, v161
	v_fmac_f32_e32 v63, v62, v62
	v_mul_f32_e32 v62, v65, v65
	v_pk_add_f32 v[66:67], v[60:61], v[72:73]
	v_fmac_f32_e32 v62, v64, v64
	v_cvt_pk_bf16_f32 v59, v64, v65
	v_add_f32_e32 v62, v63, v62
	v_mul_f32_e32 v63, v69, v69
	v_mul_f32_e32 v64, v67, v67
	v_fmac_f32_e32 v63, v68, v68
	v_fmac_f32_e32 v64, v66, v66
	v_add_f32_e32 v63, v63, v64
	v_add_f32_e32 v70, v62, v63
	v_lshlrev_b32_e32 v62, 16, v146
	v_and_b32_e32 v63, 0xffff0000, v146
	v_lshlrev_b32_e32 v64, 16, v147
	v_and_b32_e32 v65, 0xffff0000, v147
	v_cvt_pk_bf16_f32 v60, v68, v69
	v_cvt_pk_bf16_f32 v61, v66, v67
	v_lshlrev_b32_e32 v66, 16, v148
	v_and_b32_e32 v67, 0xffff0000, v148
	v_pk_add_f32 v[56:57], v[56:57], v[64:65]
	v_pk_add_f32 v[54:55], v[54:55], v[62:63]
	v_lshlrev_b32_e32 v68, 16, v149
	v_and_b32_e32 v69, 0xffff0000, v149
	v_pk_add_f32 v[64:65], v[50:51], v[66:67]
	v_mul_f32_e32 v50, v55, v55
	v_mul_f32_e32 v51, v57, v57
	v_pk_add_f32 v[62:63], v[52:53], v[68:69]
	v_fmac_f32_e32 v50, v54, v54
	v_fmac_f32_e32 v51, v56, v56
	v_add_f32_e32 v50, v50, v51
	v_mul_f32_e32 v51, v65, v65
	v_mul_f32_e32 v52, v63, v63
	v_fmac_f32_e32 v51, v64, v64
	v_fmac_f32_e32 v52, v62, v62
	v_add_f32_e32 v51, v51, v52
	v_add_f32_e32 v50, v50, v51
	v_add_f32_e32 v53, v70, v50
	v_mov_b32_e32 v68, v53
	s_nop 1
	v_permlane16_swap_b32_e32 v53, v68
	v_lshl_add_u64 v[50:51], s[58:59], 0, v[226:227]
	v_lshl_add_u64 v[66:67], v[204:205], 1, v[50:51]
	global_store_dwordx4 v[66:67], v[58:61], off
	v_cvt_pk_bf16_f32 v52, v54, v55
	s_waitcnt lgkmcnt(0)
	v_add_f32_e32 v50, v53, v68
	v_mov_b32_e32 v51, v50
	s_nop 1
	v_permlane32_swap_b32_e32 v50, v51
	v_cvt_pk_bf16_f32 v53, v56, v57
	v_cvt_pk_bf16_f32 v54, v64, v65
	v_cvt_pk_bf16_f32 v55, v62, v63
	global_store_dwordx4 v[66:67], v[52:55], off offset:256
	s_and_saveexec_b64 s[88:89], s[4:5]
	s_cbranch_execz .LBB0_333
	s_waitcnt lgkmcnt(0)
	v_add_f32_e32 v52, v50, v51
	v_lshlrev_b64 v[50:51], 6, v[224:225]
	v_lshl_add_u64 v[50:51], s[56:57], 0, v[50:51]
	v_lshl_add_u64 v[50:51], s[86:87], 2, v[50:51]
	s_lshl_b32 s12, s29, 2
	v_lshl_add_u64 v[50:51], v[50:51], 0, s[12:13]
	global_store_dword v[50:51], v52, off
; __device__ __forceinline__ unsigned cvt_pk_bf16(float lo, float hi) { unsigned r; asm volatile("v_cvt_pk_bf16_f32 %0, %1, %2" : "=v"(r) : "v"(lo), "v"(hi)); return r; }
;     __device__ __forceinline__ void operator()(const f32x4 (&acc)[2][2][4][2], const Unit& u, int wr, int wc, int fr, int fq) const {
;     ...
;             for (int m = 0; m < 4; ++m) { const int row = row0 + ai * HALF + m * 16; float s = 0.f;
; #pragma unroll
;                 for (int bj = 0; bj < 2; ++bj) { const size_t off = (size_t)row * 1024 + col0 + bj * HALF;
;                     const u32x4 h4 = hv[ai][m][bj];
;                     const f32x4 b0 = {__uint_as_float(h4.x << 16), __uint_as_float(h4.x & 0xffff0000u), __uint_as_float(h4.y << 16), __uint_as_float(h4.y & 0xffff0000u)};
;                     const f32x4 b1 = {__uint_as_float(h4.z << 16), __uint_as_float(h4.z & 0xffff0000u), __uint_as_float(h4.w << 16), __uint_as_float(h4.w & 0xffff0000u)};
;                     const f32x4 v0 = acc[ai][bj][m][0] + b0, v1 = acc[ai][bj][m][1] + b1;
;                     u32x4 w; w.x = cvt_pk_bf16(v0[0], v0[1]); w.y = cvt_pk_bf16(v0[2], v0[3]); w.z = cvt_pk_bf16(v1[0], v1[1]); w.w = cvt_pk_bf16(v1[2], v1[3]);
;                     *(u32x4*)(hb + off) = w;
;                     s += ((v0[0] * v0[0] + v0[1] * v0[1]) + (v0[2] * v0[2] + v0[3] * v0[3])) + ((v1[0] * v1[0] + v1[1] * v1[1]) + (v1[2] * v1[2] + v1[3] * v1[3])); }
;                 s += __shfl_xor(s, 16); s += __shfl_xor(s, 32);
;                 if (fq == 0) ssq[(size_t)row * 16 + u.pn * 4 + wc] = s; }
.LBB0_333:
	s_or_b64 exec, exec, s[88:89]
	s_waitcnt vmcnt(19)
	v_lshlrev_b32_e32 v50, 16, v142
	s_waitcnt lgkmcnt(0)
	v_and_b32_e32 v51, 0xffff0000, v142
	v_lshlrev_b32_e32 v52, 16, v143
	v_and_b32_e32 v53, 0xffff0000, v143
	v_lshlrev_b32_e32 v54, 16, v144
	v_and_b32_e32 v55, 0xffff0000, v144
	v_pk_add_f32 v[46:47], v[46:47], v[50:51]
	v_pk_add_f32 v[48:49], v[48:49], v[52:53]
	v_pk_add_f32 v[52:53], v[42:43], v[54:55]
	v_cvt_pk_bf16_f32 v42, v46, v47
	v_mul_f32_e32 v47, v47, v47
	v_lshlrev_b32_e32 v56, 16, v145
	v_and_b32_e32 v57, 0xffff0000, v145
	v_fmac_f32_e32 v47, v46, v46
	v_mul_f32_e32 v46, v49, v49
	v_pk_add_f32 v[50:51], v[44:45], v[56:57]
	v_fmac_f32_e32 v46, v48, v48
	v_cvt_pk_bf16_f32 v43, v48, v49
	v_add_f32_e32 v46, v47, v46
	v_mul_f32_e32 v47, v53, v53
	v_mul_f32_e32 v48, v51, v51
	v_fmac_f32_e32 v47, v52, v52
	v_fmac_f32_e32 v48, v50, v50
	v_add_f32_e32 v47, v47, v48
	v_add_f32_e32 v54, v46, v47
	v_lshlrev_b32_e32 v46, 16, v138
	v_and_b32_e32 v47, 0xffff0000, v138
	v_lshlrev_b32_e32 v48, 16, v139
	v_and_b32_e32 v49, 0xffff0000, v139
	v_cvt_pk_bf16_f32 v44, v52, v53
	v_cvt_pk_bf16_f32 v45, v50, v51
	v_lshlrev_b32_e32 v50, 16, v140
	v_and_b32_e32 v51, 0xffff0000, v140
	v_pk_add_f32 v[40:41], v[40:41], v[48:49]
	v_pk_add_f32 v[38:39], v[38:39], v[46:47]
	v_lshlrev_b32_e32 v52, 16, v141
	v_and_b32_e32 v53, 0xffff0000, v141
	v_pk_add_f32 v[48:49], v[34:35], v[50:51]
	v_mul_f32_e32 v34, v39, v39
	v_mul_f32_e32 v35, v41, v41
	v_pk_add_f32 v[46:47], v[36:37], v[52:53]
	v_fmac_f32_e32 v34, v38, v38
	v_fmac_f32_e32 v35, v40, v40
	v_add_f32_e32 v34, v34, v35
	v_mul_f32_e32 v35, v49, v49
	v_mul_f32_e32 v36, v47, v47
	v_fmac_f32_e32 v35, v48, v48
	v_fmac_f32_e32 v36, v46, v46
	v_add_f32_e32 v35, v35, v36
	v_add_f32_e32 v34, v34, v35
	v_add_f32_e32 v37, v54, v34
	v_mov_b32_e32 v52, v37
	s_nop 1
	v_permlane16_swap_b32_e32 v37, v52
	v_lshl_add_u64 v[34:35], s[58:59], 0, v[222:223]
	v_lshl_add_u64 v[50:51], v[204:205], 1, v[34:35]
	global_store_dwordx4 v[50:51], v[42:45], off
	v_cvt_pk_bf16_f32 v36, v38, v39
	s_waitcnt lgkmcnt(0)
	v_add_f32_e32 v34, v37, v52
	v_mov_b32_e32 v35, v34
	s_nop 1
	v_permlane32_swap_b32_e32 v34, v35
	v_cvt_pk_bf16_f32 v37, v40, v41
	v_cvt_pk_bf16_f32 v38, v48, v49
	v_cvt_pk_bf16_f32 v39, v46, v47
	global_store_dwordx4 v[50:51], v[36:39], off offset:256
	s_and_saveexec_b64 s[88:89], s[4:5]
	s_cbranch_execz .LBB0_335
	s_waitcnt lgkmcnt(0)
	v_add_f32_e32 v36, v34, v35
	v_lshlrev_b64 v[34:35], 6, v[220:221]
	v_lshl_add_u64 v[34:35], s[56:57], 0, v[34:35]
	v_lshl_add_u64 v[34:35], s[86:87], 2, v[34:35]
	s_lshl_b32 s12, s29, 2
	v_lshl_add_u64 v[34:35], v[34:35], 0, s[12:13]
	global_store_dword v[34:35], v36, off
; __device__ __forceinline__ unsigned cvt_pk_bf16(float lo, float hi) { unsigned r; asm volatile("v_cvt_pk_bf16_f32 %0, %1, %2" : "=v"(r) : "v"(lo), "v"(hi)); return r; }
;     __device__ __forceinline__ void operator()(const f32x4 (&acc)[2][2][4][2], const Unit& u, int wr, int wc, int fr, int fq) const {
;     ...
;             for (int m = 0; m < 4; ++m) { const int row = row0 + ai * HALF + m * 16; float s = 0.f;
; #pragma unroll
;                 for (int bj = 0; bj < 2; ++bj) { const size_t off = (size_t)row * 1024 + col0 + bj * HALF;
;                     const u32x4 h4 = hv[ai][m][bj];
;                     const f32x4 b0 = {__uint_as_float(h4.x << 16), __uint_as_float(h4.x & 0xffff0000u), __uint_as_float(h4.y << 16), __uint_as_float(h4.y & 0xffff0000u)};
;                     const f32x4 b1 = {__uint_as_float(h4.z << 16), __uint_as_float(h4.z & 0xffff0000u), __uint_as_float(h4.w << 16), __uint_as_float(h4.w & 0xffff0000u)};
;                     const f32x4 v0 = acc[ai][bj][m][0] + b0, v1 = acc[ai][bj][m][1] + b1;
;                     u32x4 w; w.x = cvt_pk_bf16(v0[0], v0[1]); w.y = cvt_pk_bf16(v0[2], v0[3]); w.z = cvt_pk_bf16(v1[0], v1[1]); w.w = cvt_pk_bf16(v1[2], v1[3]);
;                     *(u32x4*)(hb + off) = w;
;                     s += ((v0[0] * v0[0] + v0[1] * v0[1]) + (v0[2] * v0[2] + v0[3] * v0[3])) + ((v1[0] * v1[0] + v1[1] * v1[1]) + (v1[2] * v1[2] + v1[3] * v1[3])); }
;                 s += __shfl_xor(s, 16); s += __shfl_xor(s, 32);
;                 if (fq == 0) ssq[(size_t)row * 16 + u.pn * 4 + wc] = s; }
.LBB0_335:
	s_or_b64 exec, exec, s[88:89]
	s_waitcnt vmcnt(20)
	v_lshlrev_b32_e32 v34, 16, v126
	s_waitcnt lgkmcnt(0)
	v_and_b32_e32 v35, 0xffff0000, v126
	v_lshlrev_b32_e32 v36, 16, v127
	v_and_b32_e32 v37, 0xffff0000, v127
	v_lshlrev_b32_e32 v38, 16, v128
	v_and_b32_e32 v39, 0xffff0000, v128
	v_pk_add_f32 v[30:31], v[30:31], v[34:35]
	v_pk_add_f32 v[32:33], v[32:33], v[36:37]
	v_pk_add_f32 v[36:37], v[26:27], v[38:39]
	v_cvt_pk_bf16_f32 v26, v30, v31
	v_mul_f32_e32 v31, v31, v31
	v_lshlrev_b32_e32 v40, 16, v129
	v_and_b32_e32 v41, 0xffff0000, v129
	v_fmac_f32_e32 v31, v30, v30
	v_mul_f32_e32 v30, v33, v33
	v_pk_add_f32 v[34:35], v[28:29], v[40:41]
	v_fmac_f32_e32 v30, v32, v32
	v_cvt_pk_bf16_f32 v27, v32, v33
	v_add_f32_e32 v30, v31, v30
	v_mul_f32_e32 v31, v37, v37
	v_mul_f32_e32 v32, v35, v35
	v_fmac_f32_e32 v31, v36, v36
	v_fmac_f32_e32 v32, v34, v34
	v_add_f32_e32 v31, v31, v32
	v_add_f32_e32 v38, v30, v31
	v_lshlrev_b32_e32 v30, 16, v114
	v_and_b32_e32 v31, 0xffff0000, v114
	v_lshlrev_b32_e32 v32, 16, v115
	v_and_b32_e32 v33, 0xffff0000, v115
	v_cvt_pk_bf16_f32 v28, v36, v37
	v_cvt_pk_bf16_f32 v29, v34, v35
	v_lshlrev_b32_e32 v34, 16, v116
	v_and_b32_e32 v35, 0xffff0000, v116
	v_pk_add_f32 v[24:25], v[24:25], v[32:33]
	v_pk_add_f32 v[22:23], v[22:23], v[30:31]
	v_lshlrev_b32_e32 v36, 16, v117
	v_and_b32_e32 v37, 0xffff0000, v117
	v_pk_add_f32 v[32:33], v[18:19], v[34:35]
	v_mul_f32_e32 v18, v23, v23
	v_mul_f32_e32 v19, v25, v25
	v_pk_add_f32 v[30:31], v[20:21], v[36:37]
	v_fmac_f32_e32 v18, v22, v22
	v_fmac_f32_e32 v19, v24, v24
	v_add_f32_e32 v18, v18, v19
	v_mul_f32_e32 v19, v33, v33
	v_mul_f32_e32 v20, v31, v31
	v_fmac_f32_e32 v19, v32, v32
	v_fmac_f32_e32 v20, v30, v30
	v_add_f32_e32 v19, v19, v20
	v_add_f32_e32 v18, v18, v19
	v_add_f32_e32 v21, v38, v18
	v_mov_b32_e32 v36, v21
	s_nop 1
	v_permlane16_swap_b32_e32 v21, v36
	v_lshl_add_u64 v[18:19], s[58:59], 0, v[218:219]
	v_lshl_add_u64 v[34:35], v[204:205], 1, v[18:19]
	global_store_dwordx4 v[34:35], v[26:29], off
	v_cvt_pk_bf16_f32 v20, v22, v23
	s_waitcnt lgkmcnt(0)
	v_add_f32_e32 v18, v21, v36
	v_mov_b32_e32 v19, v18
	s_nop 1
	v_permlane32_swap_b32_e32 v18, v19
	v_cvt_pk_bf16_f32 v21, v24, v25
	v_cvt_pk_bf16_f32 v22, v32, v33
	v_cvt_pk_bf16_f32 v23, v30, v31
	global_store_dwordx4 v[34:35], v[20:23], off offset:256
	s_and_saveexec_b64 s[88:89], s[4:5]
	s_cbranch_execz .LBB0_337
	s_waitcnt lgkmcnt(0)
	v_add_f32_e32 v20, v18, v19
	v_lshlrev_b64 v[18:19], 6, v[216:217]
	v_lshl_add_u64 v[18:19], s[56:57], 0, v[18:19]
	v_lshl_add_u64 v[18:19], s[86:87], 2, v[18:19]
	s_lshl_b32 s12, s29, 2
	v_lshl_add_u64 v[18:19], v[18:19], 0, s[12:13]
	global_store_dword v[18:19], v20, off
.LBB0_337:
	s_or_b64 exec, exec, s[88:89]
	s_waitcnt vmcnt(21)
	v_lshlrev_b32_e32 v18, 16, v130
	s_waitcnt lgkmcnt(0)
	v_and_b32_e32 v19, 0xffff0000, v130
	v_lshlrev_b32_e32 v20, 16, v131
	v_and_b32_e32 v21, 0xffff0000, v131
	v_lshlrev_b32_e32 v22, 16, v132
	v_and_b32_e32 v23, 0xffff0000, v132
	v_pk_add_f32 v[14:15], v[14:15], v[18:19]
	v_pk_add_f32 v[16:17], v[16:17], v[20:21]
	v_pk_add_f32 v[20:21], v[10:11], v[22:23]
	v_cvt_pk_bf16_f32 v10, v14, v15
	v_mul_f32_e32 v15, v15, v15
	v_lshlrev_b32_e32 v24, 16, v133
	v_and_b32_e32 v25, 0xffff0000, v133
	v_fmac_f32_e32 v15, v14, v14
	v_mul_f32_e32 v14, v17, v17
	v_pk_add_f32 v[18:19], v[12:13], v[24:25]
	v_fmac_f32_e32 v14, v16, v16
	v_cvt_pk_bf16_f32 v11, v16, v17
	v_add_f32_e32 v14, v15, v14
	v_mul_f32_e32 v15, v21, v21
	v_mul_f32_e32 v16, v19, v19
	v_fmac_f32_e32 v15, v20, v20
	v_fmac_f32_e32 v16, v18, v18
	v_add_f32_e32 v15, v15, v16
	v_add_f32_e32 v22, v14, v15
	v_lshlrev_b32_e32 v14, 16, v122
	v_and_b32_e32 v15, 0xffff0000, v122
	v_lshlrev_b32_e32 v16, 16, v123
	v_and_b32_e32 v17, 0xffff0000, v123
	v_cvt_pk_bf16_f32 v12, v20, v21
	v_cvt_pk_bf16_f32 v13, v18, v19
	v_lshlrev_b32_e32 v18, 16, v124
	v_and_b32_e32 v19, 0xffff0000, v124
	v_pk_add_f32 v[8:9], v[8:9], v[16:17]
	v_pk_add_f32 v[6:7], v[6:7], v[14:15]
	v_lshlrev_b32_e32 v20, 16, v125
	v_and_b32_e32 v21, 0xffff0000, v125
	v_pk_add_f32 v[16:17], v[2:3], v[18:19]
	v_mul_f32_e32 v2, v7, v7
	v_mul_f32_e32 v3, v9, v9
	v_pk_add_f32 v[14:15], v[4:5], v[20:21]
	v_fmac_f32_e32 v2, v6, v6
	v_fmac_f32_e32 v3, v8, v8
	v_add_f32_e32 v2, v2, v3
	v_mul_f32_e32 v3, v17, v17
	v_mul_f32_e32 v4, v15, v15
	v_fmac_f32_e32 v3, v16, v16
	v_fmac_f32_e32 v4, v14, v14
	v_add_f32_e32 v3, v3, v4
	v_add_f32_e32 v2, v2, v3
	v_add_f32_e32 v5, v22, v2
	v_mov_b32_e32 v20, v5
	s_nop 1
	v_permlane16_swap_b32_e32 v5, v20
	v_lshl_add_u64 v[2:3], s[58:59], 0, v[214:215]
	v_lshl_add_u64 v[18:19], v[204:205], 1, v[2:3]
	global_store_dwordx4 v[18:19], v[10:13], off
	v_cvt_pk_bf16_f32 v4, v6, v7
	s_waitcnt lgkmcnt(0)
	v_add_f32_e32 v2, v5, v20
	v_mov_b32_e32 v3, v2
	s_nop 1
	v_permlane32_swap_b32_e32 v2, v3
	v_cvt_pk_bf16_f32 v5, v8, v9
	v_cvt_pk_bf16_f32 v6, v16, v17
	v_cvt_pk_bf16_f32 v7, v14, v15
	global_store_dwordx4 v[18:19], v[4:7], off offset:256
	s_and_saveexec_b64 s[88:89], s[4:5]
	s_cbranch_execz .LBB0_339
	s_waitcnt lgkmcnt(0)
	v_add_f32_e32 v4, v2, v3
	v_lshlrev_b64 v[2:3], 6, v[212:213]
	v_lshl_add_u64 v[2:3], s[56:57], 0, v[2:3]
	v_lshl_add_u64 v[2:3], s[86:87], 2, v[2:3]
	s_lshl_b32 s12, s29, 2
	v_lshl_add_u64 v[2:3], v[2:3], 0, s[12:13]
	global_store_dword v[2:3], v4, off
